# phase-0 weight conversion loop: counted vmcnt(1) at loop top (do not wait for the previous tile's store ack); plus seam 2 and final seam prefetch
# speedup vs baseline: 1.0008x; 1.0008x over previous
.LBB0_49:
	s_mov_b32 s1, 0
	s_mul_i32 s18, s8, s0
	s_mov_b32 s19, s1
	s_lshl_b64 s[18:19], s[18:19], 2
	s_add_u32 s9, s6, s18
	s_addc_u32 s17, s7, s19
	s_ashr_i32 s15, s14, 31
	s_lshl_b64 s[6:7], s[14:15], 2
	v_add_u32_e32 v1, 32, v194
	s_add_u32 s6, s9, s6
	v_mul_u32_u24_e32 v2, s8, v1
	s_addc_u32 s7, s17, s7
	v_lshlrev_b32_e32 v10, 2, v2
	v_mov_b32_e32 v11, 0
	v_and_b32_e32 v12, 60, v164
	v_lshl_add_u64 v[2:3], s[6:7], 0, v[10:11]
	v_lshlrev_b32_e32 v10, 2, v12
	v_lshl_add_u64 v[14:15], v[2:3], 0, v[10:11]
	v_mul_u32_u24_e32 v2, s8, v194
	v_lshlrev_b32_e32 v2, 2, v2
	v_mov_b32_e32 v3, v11
	v_lshl_add_u64 v[2:3], s[6:7], 0, v[2:3]
	v_lshl_add_u64 v[16:17], v[2:3], 0, v[10:11]
	global_load_dwordx4 v[6:9], v[14:15], off
	global_load_dwordx4 v[2:5], v[16:17], off
	s_add_u32 s6, s34, s4
	s_addc_u32 s7, s35, s5
	s_mul_hi_i32 s5, s20, s16
	s_mul_i32 s4, s20, s16
	v_mul_u32_u24_e32 v13, 0x104, v194
	s_lshl_b64 s[4:5], s[4:5], 1
	v_add3_u32 v16, 0, v13, v10
	v_lshlrev_b32_e32 v10, 3, v146
	s_add_u32 s6, s6, s4
	v_and_b32_e32 v10, 56, v10
	s_addc_u32 s7, s7, s5
	s_lshl_b64 s[4:5], s[0:1], 1
	v_mul_u32_u24_e32 v13, 0x104, v10
	v_lshlrev_b32_e32 v14, 2, v128
	s_add_u32 s4, s6, s4
	v_add3_u32 v17, 0, v13, v14
	s_addc_u32 s5, s7, s5
	v_add_u32_e32 v18, 0x2080, v16
	v_add_u32_e32 v19, 0x2088, v16
	v_lshlrev_b32_e32 v12, 2, v12
	v_lshlrev_b32_e32 v14, 1, v10
	v_add_u32_e32 v20, 0x400, v17
	v_mov_b32_e32 v15, v11
	s_mov_b32 s21, s2
	s_waitcnt vmcnt(0)
	s_branch .LBB0_53

.LBB0_53:
	s_add_i32 s21, s21, s3
	s_cmpk_gt_i32 s21, 0x83f
	s_cselect_b64 s[6:7], -1, 0
	s_mov_b64 s[8:9], 0
	s_and_b64 vcc, exec, s[6:7]
	s_mov_b32 s22, 0
	s_waitcnt vmcnt(1)
	ds_write2_b32 v16, v2, v3 offset1:1
	ds_write2_b32 v18, v6, v7 offset1:1
	ds_write2_b32 v16, v4, v5 offset0:2 offset1:3
	ds_write2_b32 v19, v8, v9 offset1:1
	s_cbranch_vccnz .LBB0_52
	s_add_i32 s0, s21, 0x580
	s_cmpk_lt_i32 s21, 0x580
	s_cselect_b32 s17, s21, s0
	s_cmpk_gt_i32 s17, 0xaff
	s_mov_b64 s[14:15], -1
	s_cbranch_scc0 .LBB0_56
	s_add_i32 s0, s17, 0xf500
	s_and_b32 s8, s0, 0xffff
	s_mul_i32 s8, s8, 0xba2f
	s_lshr_b32 s8, s8, 21
	s_mul_i32 s9, s8, 44
	s_sub_i32 s0, s0, s9
	s_lshl_b32 s0, s0, 6
	s_lshl_b32 s23, s8, 6
	s_and_b32 s0, s0, 0xffc0
	s_mov_b64 s[14:15], 0
	s_mov_b64 s[8:9], s[40:41]
